# scan recurrence rewritten: LDS operands fetched two steps ahead into rotating register sets, state parking in DPP wait slots; plus attention K/V prefetch waits moved to the LDS-store point
# speedup vs baseline: 1.0195x; 1.0195x over previous
.LBB0_1047:
	s_and_b32 s1, s0, 1
	s_mul_i32 s7, s1, 0x5000
	v_lshl_add_u32 v9, v169, 4, s7
	v_lshl_add_u32 v10, v6, 2, s7
	ds_read_b128 v[44:47], v9 offset:256
	ds_read_b128 v[40:43], v9
	ds_read_b128 v[52:55], v9 offset:768
	ds_read_b32 v56, v10 offset:1024
	ds_read_b128 v[48:51], v9 offset:512
	ds_read_b128 v[80:83], v9 offset:1536
	ds_read_b128 v[76:79], v9 offset:1280
	ds_read_b128 v[88:91], v9 offset:2048
	ds_read_b32 v92, v10 offset:2304
	ds_read_b128 v[84:87], v9 offset:1792
	s_mul_i32 s1, s1, 0x9000
	v_add_u32_e32 v11, s1, v7
	v_add_u32_e32 v8, 0xb000, v11
	s_waitcnt lgkmcnt(5)
	v_pk_mul_f32 v[58:59], v[44:45], v[2:3]
	v_pk_mul_f32 v[60:61], v[40:41], v[2:3]
	v_pk_fma_f32 v[58:59], v[46:47], v[4:5], v[58:59]
	v_pk_mul_f32 v[62:63], v[42:43], v[4:5]
	v_add_f32_e32 v64, v58, v59
	v_pk_fma_f32 v[60:61], v[52:53], v[56:57], v[60:61] op_sel_hi:[1,0,1]
	v_pk_fma_f32 v[62:63], v[54:55], v[56:57], v[62:63] op_sel_hi:[1,0,1]
	v_add_f32_dpp v65, v64, v64 quad_perm:[1,0,3,2] row_mask:0xf bank_mask:0xf bound_ctrl:1
	ds_read_b128 v[100:103], v9 offset:2816
	ds_read_b128 v[96:99], v9 offset:2560
	v_add_f32_dpp v64, v65, v65 quad_perm:[2,3,0,1] row_mask:0xf bank_mask:0xf bound_ctrl:1
	ds_read_b128 v[108:111], v9 offset:3328
	ds_read_b32 v112, v10 offset:3584
	v_add_f32_dpp v65, v64, v64 row_half_mirror row_mask:0xf bank_mask:0xf bound_ctrl:1
	ds_read_b128 v[104:107], v9 offset:3072
	s_nop 0
	v_add_f32_dpp v66, v65, v65 row_mirror row_mask:0xf bank_mask:0xf bound_ctrl:1
	v_pk_fma_f32 v[2:3], v[48:49], v[66:67], v[60:61] op_sel_hi:[1,0,1]
	v_pk_fma_f32 v[4:5], v[50:51], v[66:67], v[62:63] op_sel_hi:[1,0,1]
	s_waitcnt lgkmcnt(5)
	v_pk_mul_f32 v[58:59], v[80:81], v[2:3]
	v_pk_mul_f32 v[60:61], v[76:77], v[2:3]
	v_pk_fma_f32 v[58:59], v[82:83], v[4:5], v[58:59]
	v_pk_mul_f32 v[62:63], v[78:79], v[4:5]
	v_add_f32_e32 v64, v58, v59
	v_pk_fma_f32 v[60:61], v[88:89], v[92:93], v[60:61] op_sel_hi:[1,0,1]
	v_pk_fma_f32 v[62:63], v[90:91], v[92:93], v[62:63] op_sel_hi:[1,0,1]
	v_add_f32_dpp v65, v64, v64 quad_perm:[1,0,3,2] row_mask:0xf bank_mask:0xf bound_ctrl:1
	v_cvt_pk_bf16_f32 v68, v2, v3
	v_cvt_pk_bf16_f32 v69, v4, v5
	v_add_f32_dpp v64, v65, v65 quad_perm:[2,3,0,1] row_mask:0xf bank_mask:0xf bound_ctrl:1
	ds_write_b64 v11, v[68:69] offset:45056
	ds_read_b128 v[44:47], v9 offset:4096
	v_add_f32_dpp v65, v64, v64 row_half_mirror row_mask:0xf bank_mask:0xf bound_ctrl:1
	ds_read_b128 v[40:43], v9 offset:3840
	ds_read_b128 v[52:55], v9 offset:4608
	v_add_f32_dpp v66, v65, v65 row_mirror row_mask:0xf bank_mask:0xf bound_ctrl:1
	v_pk_fma_f32 v[2:3], v[84:85], v[66:67], v[60:61] op_sel_hi:[1,0,1]
	v_pk_fma_f32 v[4:5], v[86:87], v[66:67], v[62:63] op_sel_hi:[1,0,1]
	ds_read_b32 v56, v10 offset:4864
	ds_read_b128 v[48:51], v9 offset:4352
	s_waitcnt lgkmcnt(6)
	v_pk_mul_f32 v[58:59], v[100:101], v[2:3]
	v_pk_mul_f32 v[60:61], v[96:97], v[2:3]
	v_pk_fma_f32 v[58:59], v[102:103], v[4:5], v[58:59]
	v_pk_mul_f32 v[62:63], v[98:99], v[4:5]
	v_add_f32_e32 v64, v58, v59
	v_pk_fma_f32 v[60:61], v[108:109], v[112:113], v[60:61] op_sel_hi:[1,0,1]
	v_pk_fma_f32 v[62:63], v[110:111], v[112:113], v[62:63] op_sel_hi:[1,0,1]
	v_add_f32_dpp v65, v64, v64 quad_perm:[1,0,3,2] row_mask:0xf bank_mask:0xf bound_ctrl:1
	v_cvt_pk_bf16_f32 v70, v2, v3
	v_cvt_pk_bf16_f32 v71, v4, v5
	v_add_f32_dpp v64, v65, v65 quad_perm:[2,3,0,1] row_mask:0xf bank_mask:0xf bound_ctrl:1
	ds_write_b64 v11, v[70:71] offset:47360
	ds_read_b128 v[80:83], v9 offset:5376
	v_add_f32_dpp v65, v64, v64 row_half_mirror row_mask:0xf bank_mask:0xf bound_ctrl:1
	ds_read_b128 v[76:79], v9 offset:5120
	ds_read_b128 v[88:91], v9 offset:5888
	v_add_f32_dpp v66, v65, v65 row_mirror row_mask:0xf bank_mask:0xf bound_ctrl:1
	v_pk_fma_f32 v[2:3], v[104:105], v[66:67], v[60:61] op_sel_hi:[1,0,1]
	v_pk_fma_f32 v[4:5], v[106:107], v[66:67], v[62:63] op_sel_hi:[1,0,1]
	ds_read_b32 v92, v10 offset:6144
	ds_read_b128 v[84:87], v9 offset:5632
	s_waitcnt lgkmcnt(6)
	v_pk_mul_f32 v[58:59], v[44:45], v[2:3]
	v_pk_mul_f32 v[60:61], v[40:41], v[2:3]
	v_pk_fma_f32 v[58:59], v[46:47], v[4:5], v[58:59]
	v_pk_mul_f32 v[62:63], v[42:43], v[4:5]
	v_add_f32_e32 v64, v58, v59
	v_pk_fma_f32 v[60:61], v[52:53], v[56:57], v[60:61] op_sel_hi:[1,0,1]
	v_pk_fma_f32 v[62:63], v[54:55], v[56:57], v[62:63] op_sel_hi:[1,0,1]
	v_add_f32_dpp v65, v64, v64 quad_perm:[1,0,3,2] row_mask:0xf bank_mask:0xf bound_ctrl:1
	v_cvt_pk_bf16_f32 v68, v2, v3
	v_cvt_pk_bf16_f32 v69, v4, v5
	v_add_f32_dpp v64, v65, v65 quad_perm:[2,3,0,1] row_mask:0xf bank_mask:0xf bound_ctrl:1
	ds_write_b64 v11, v[68:69] offset:49664
	ds_read_b128 v[100:103], v9 offset:6656
	v_add_f32_dpp v65, v64, v64 row_half_mirror row_mask:0xf bank_mask:0xf bound_ctrl:1
	ds_read_b128 v[96:99], v9 offset:6400
	ds_read_b128 v[108:111], v9 offset:7168
	v_add_f32_dpp v66, v65, v65 row_mirror row_mask:0xf bank_mask:0xf bound_ctrl:1
	v_pk_fma_f32 v[2:3], v[48:49], v[66:67], v[60:61] op_sel_hi:[1,0,1]
	v_pk_fma_f32 v[4:5], v[50:51], v[66:67], v[62:63] op_sel_hi:[1,0,1]
	ds_read_b32 v112, v10 offset:7424
	ds_read_b128 v[104:107], v9 offset:6912
	s_waitcnt lgkmcnt(6)
	v_pk_mul_f32 v[58:59], v[80:81], v[2:3]
	v_pk_mul_f32 v[60:61], v[76:77], v[2:3]
	v_pk_fma_f32 v[58:59], v[82:83], v[4:5], v[58:59]
	v_pk_mul_f32 v[62:63], v[78:79], v[4:5]
	v_add_f32_e32 v64, v58, v59
	v_pk_fma_f32 v[60:61], v[88:89], v[92:93], v[60:61] op_sel_hi:[1,0,1]
	v_pk_fma_f32 v[62:63], v[90:91], v[92:93], v[62:63] op_sel_hi:[1,0,1]
	v_add_f32_dpp v65, v64, v64 quad_perm:[1,0,3,2] row_mask:0xf bank_mask:0xf bound_ctrl:1
	v_cvt_pk_bf16_f32 v70, v2, v3
	v_cvt_pk_bf16_f32 v71, v4, v5
	v_add_f32_dpp v64, v65, v65 quad_perm:[2,3,0,1] row_mask:0xf bank_mask:0xf bound_ctrl:1
	ds_write_b64 v11, v[70:71] offset:51968
	ds_read_b128 v[44:47], v9 offset:7936
	v_add_f32_dpp v65, v64, v64 row_half_mirror row_mask:0xf bank_mask:0xf bound_ctrl:1
	ds_read_b128 v[40:43], v9 offset:7680
	ds_read_b128 v[52:55], v9 offset:8448
	v_add_f32_dpp v66, v65, v65 row_mirror row_mask:0xf bank_mask:0xf bound_ctrl:1
	v_pk_fma_f32 v[2:3], v[84:85], v[66:67], v[60:61] op_sel_hi:[1,0,1]
	v_pk_fma_f32 v[4:5], v[86:87], v[66:67], v[62:63] op_sel_hi:[1,0,1]
	ds_read_b32 v56, v10 offset:8704
	ds_read_b128 v[48:51], v9 offset:8192
	s_waitcnt lgkmcnt(6)
	v_pk_mul_f32 v[58:59], v[100:101], v[2:3]
	v_pk_mul_f32 v[60:61], v[96:97], v[2:3]
	v_pk_fma_f32 v[58:59], v[102:103], v[4:5], v[58:59]
	v_pk_mul_f32 v[62:63], v[98:99], v[4:5]
	v_add_f32_e32 v64, v58, v59
	v_pk_fma_f32 v[60:61], v[108:109], v[112:113], v[60:61] op_sel_hi:[1,0,1]
	v_pk_fma_f32 v[62:63], v[110:111], v[112:113], v[62:63] op_sel_hi:[1,0,1]
	v_add_f32_dpp v65, v64, v64 quad_perm:[1,0,3,2] row_mask:0xf bank_mask:0xf bound_ctrl:1
	v_cvt_pk_bf16_f32 v68, v2, v3
	v_cvt_pk_bf16_f32 v69, v4, v5
	v_add_f32_dpp v64, v65, v65 quad_perm:[2,3,0,1] row_mask:0xf bank_mask:0xf bound_ctrl:1
	ds_write_b64 v11, v[68:69] offset:54272
	ds_read_b128 v[80:83], v9 offset:9216
	v_add_f32_dpp v65, v64, v64 row_half_mirror row_mask:0xf bank_mask:0xf bound_ctrl:1
	ds_read_b128 v[76:79], v9 offset:8960
	ds_read_b128 v[88:91], v9 offset:9728
	v_add_f32_dpp v66, v65, v65 row_mirror row_mask:0xf bank_mask:0xf bound_ctrl:1
	v_pk_fma_f32 v[2:3], v[104:105], v[66:67], v[60:61] op_sel_hi:[1,0,1]
	v_pk_fma_f32 v[4:5], v[106:107], v[66:67], v[62:63] op_sel_hi:[1,0,1]
	ds_read_b32 v92, v10 offset:9984
	ds_read_b128 v[84:87], v9 offset:9472
	s_waitcnt lgkmcnt(6)
	v_pk_mul_f32 v[58:59], v[44:45], v[2:3]
	v_pk_mul_f32 v[60:61], v[40:41], v[2:3]
	v_pk_fma_f32 v[58:59], v[46:47], v[4:5], v[58:59]
	v_pk_mul_f32 v[62:63], v[42:43], v[4:5]
	v_add_f32_e32 v64, v58, v59
	v_pk_fma_f32 v[60:61], v[52:53], v[56:57], v[60:61] op_sel_hi:[1,0,1]
	v_pk_fma_f32 v[62:63], v[54:55], v[56:57], v[62:63] op_sel_hi:[1,0,1]
	v_add_f32_dpp v65, v64, v64 quad_perm:[1,0,3,2] row_mask:0xf bank_mask:0xf bound_ctrl:1
	v_cvt_pk_bf16_f32 v70, v2, v3
	v_cvt_pk_bf16_f32 v71, v4, v5
	v_add_f32_dpp v64, v65, v65 quad_perm:[2,3,0,1] row_mask:0xf bank_mask:0xf bound_ctrl:1
	ds_write_b64 v11, v[70:71] offset:56576
	ds_read_b128 v[100:103], v9 offset:10496
	v_add_f32_dpp v65, v64, v64 row_half_mirror row_mask:0xf bank_mask:0xf bound_ctrl:1
	ds_read_b128 v[96:99], v9 offset:10240
	ds_read_b128 v[108:111], v9 offset:11008
	v_add_f32_dpp v66, v65, v65 row_mirror row_mask:0xf bank_mask:0xf bound_ctrl:1
	v_pk_fma_f32 v[2:3], v[48:49], v[66:67], v[60:61] op_sel_hi:[1,0,1]
	v_pk_fma_f32 v[4:5], v[50:51], v[66:67], v[62:63] op_sel_hi:[1,0,1]
	ds_read_b32 v112, v10 offset:11264
	ds_read_b128 v[104:107], v9 offset:10752
	s_waitcnt lgkmcnt(6)
	v_pk_mul_f32 v[58:59], v[80:81], v[2:3]
	v_pk_mul_f32 v[60:61], v[76:77], v[2:3]
	v_pk_fma_f32 v[58:59], v[82:83], v[4:5], v[58:59]
	v_pk_mul_f32 v[62:63], v[78:79], v[4:5]
	v_add_f32_e32 v64, v58, v59
	v_pk_fma_f32 v[60:61], v[88:89], v[92:93], v[60:61] op_sel_hi:[1,0,1]
	v_pk_fma_f32 v[62:63], v[90:91], v[92:93], v[62:63] op_sel_hi:[1,0,1]
	v_add_f32_dpp v65, v64, v64 quad_perm:[1,0,3,2] row_mask:0xf bank_mask:0xf bound_ctrl:1
	v_cvt_pk_bf16_f32 v68, v2, v3
	v_cvt_pk_bf16_f32 v69, v4, v5
	v_add_f32_dpp v64, v65, v65 quad_perm:[2,3,0,1] row_mask:0xf bank_mask:0xf bound_ctrl:1
	ds_write_b64 v11, v[68:69] offset:58880
	ds_read_b128 v[44:47], v9 offset:11776
	v_add_f32_dpp v65, v64, v64 row_half_mirror row_mask:0xf bank_mask:0xf bound_ctrl:1
	ds_read_b128 v[40:43], v9 offset:11520
	ds_read_b128 v[52:55], v9 offset:12288
	v_add_f32_dpp v66, v65, v65 row_mirror row_mask:0xf bank_mask:0xf bound_ctrl:1
	v_pk_fma_f32 v[2:3], v[84:85], v[66:67], v[60:61] op_sel_hi:[1,0,1]
	v_pk_fma_f32 v[4:5], v[86:87], v[66:67], v[62:63] op_sel_hi:[1,0,1]
	ds_read_b32 v56, v10 offset:12544
	ds_read_b128 v[48:51], v9 offset:12032
	s_waitcnt lgkmcnt(6)
	v_pk_mul_f32 v[58:59], v[100:101], v[2:3]
	v_pk_mul_f32 v[60:61], v[96:97], v[2:3]
	v_pk_fma_f32 v[58:59], v[102:103], v[4:5], v[58:59]
	v_pk_mul_f32 v[62:63], v[98:99], v[4:5]
	v_add_f32_e32 v64, v58, v59
	v_pk_fma_f32 v[60:61], v[108:109], v[112:113], v[60:61] op_sel_hi:[1,0,1]
	v_pk_fma_f32 v[62:63], v[110:111], v[112:113], v[62:63] op_sel_hi:[1,0,1]
	v_add_f32_dpp v65, v64, v64 quad_perm:[1,0,3,2] row_mask:0xf bank_mask:0xf bound_ctrl:1
	v_cvt_pk_bf16_f32 v70, v2, v3
	v_cvt_pk_bf16_f32 v71, v4, v5
	v_add_f32_dpp v64, v65, v65 quad_perm:[2,3,0,1] row_mask:0xf bank_mask:0xf bound_ctrl:1
	ds_write_b64 v11, v[70:71] offset:61184
	ds_read_b128 v[80:83], v9 offset:13056
	v_add_f32_dpp v65, v64, v64 row_half_mirror row_mask:0xf bank_mask:0xf bound_ctrl:1
	ds_read_b128 v[76:79], v9 offset:12800
	ds_read_b128 v[88:91], v9 offset:13568
	v_add_f32_dpp v66, v65, v65 row_mirror row_mask:0xf bank_mask:0xf bound_ctrl:1
	v_pk_fma_f32 v[2:3], v[104:105], v[66:67], v[60:61] op_sel_hi:[1,0,1]
	v_pk_fma_f32 v[4:5], v[106:107], v[66:67], v[62:63] op_sel_hi:[1,0,1]
	ds_read_b32 v92, v10 offset:13824
	ds_read_b128 v[84:87], v9 offset:13312
	s_waitcnt lgkmcnt(6)
	v_pk_mul_f32 v[58:59], v[44:45], v[2:3]
	v_pk_mul_f32 v[60:61], v[40:41], v[2:3]
	v_pk_fma_f32 v[58:59], v[46:47], v[4:5], v[58:59]
	v_pk_mul_f32 v[62:63], v[42:43], v[4:5]
	v_add_f32_e32 v64, v58, v59
	v_pk_fma_f32 v[60:61], v[52:53], v[56:57], v[60:61] op_sel_hi:[1,0,1]
	v_pk_fma_f32 v[62:63], v[54:55], v[56:57], v[62:63] op_sel_hi:[1,0,1]
	v_add_f32_dpp v65, v64, v64 quad_perm:[1,0,3,2] row_mask:0xf bank_mask:0xf bound_ctrl:1
	v_cvt_pk_bf16_f32 v68, v2, v3
	v_cvt_pk_bf16_f32 v69, v4, v5
	v_add_f32_dpp v64, v65, v65 quad_perm:[2,3,0,1] row_mask:0xf bank_mask:0xf bound_ctrl:1
	ds_write_b64 v11, v[68:69] offset:63488
	ds_read_b128 v[100:103], v9 offset:14336
	v_add_f32_dpp v65, v64, v64 row_half_mirror row_mask:0xf bank_mask:0xf bound_ctrl:1
	ds_read_b128 v[96:99], v9 offset:14080
	ds_read_b128 v[108:111], v9 offset:14848
	v_add_f32_dpp v66, v65, v65 row_mirror row_mask:0xf bank_mask:0xf bound_ctrl:1
	v_pk_fma_f32 v[2:3], v[48:49], v[66:67], v[60:61] op_sel_hi:[1,0,1]
	v_pk_fma_f32 v[4:5], v[50:51], v[66:67], v[62:63] op_sel_hi:[1,0,1]
	ds_read_b32 v112, v10 offset:15104
	ds_read_b128 v[104:107], v9 offset:14592
	s_waitcnt lgkmcnt(6)
	v_pk_mul_f32 v[58:59], v[80:81], v[2:3]
	v_pk_mul_f32 v[60:61], v[76:77], v[2:3]
	v_pk_fma_f32 v[58:59], v[82:83], v[4:5], v[58:59]
	v_pk_mul_f32 v[62:63], v[78:79], v[4:5]
	v_add_f32_e32 v64, v58, v59
	v_pk_fma_f32 v[60:61], v[88:89], v[92:93], v[60:61] op_sel_hi:[1,0,1]
	v_pk_fma_f32 v[62:63], v[90:91], v[92:93], v[62:63] op_sel_hi:[1,0,1]
	v_add_f32_dpp v65, v64, v64 quad_perm:[1,0,3,2] row_mask:0xf bank_mask:0xf bound_ctrl:1
	v_cvt_pk_bf16_f32 v70, v2, v3
	v_cvt_pk_bf16_f32 v71, v4, v5
	v_add_f32_dpp v64, v65, v65 quad_perm:[2,3,0,1] row_mask:0xf bank_mask:0xf bound_ctrl:1
	ds_write_b64 v8, v[70:71] offset:20736
	ds_read_b128 v[44:47], v9 offset:15616
	v_add_f32_dpp v65, v64, v64 row_half_mirror row_mask:0xf bank_mask:0xf bound_ctrl:1
	ds_read_b128 v[40:43], v9 offset:15360
	ds_read_b128 v[52:55], v9 offset:16128
	v_add_f32_dpp v66, v65, v65 row_mirror row_mask:0xf bank_mask:0xf bound_ctrl:1
	v_pk_fma_f32 v[2:3], v[84:85], v[66:67], v[60:61] op_sel_hi:[1,0,1]
	v_pk_fma_f32 v[4:5], v[86:87], v[66:67], v[62:63] op_sel_hi:[1,0,1]
	ds_read_b32 v56, v10 offset:16384
	ds_read_b128 v[48:51], v9 offset:15872
	s_waitcnt lgkmcnt(6)
	v_pk_mul_f32 v[58:59], v[100:101], v[2:3]
	v_pk_mul_f32 v[60:61], v[96:97], v[2:3]
	v_pk_fma_f32 v[58:59], v[102:103], v[4:5], v[58:59]
	v_pk_mul_f32 v[62:63], v[98:99], v[4:5]
	v_add_f32_e32 v64, v58, v59
	v_pk_fma_f32 v[60:61], v[108:109], v[112:113], v[60:61] op_sel_hi:[1,0,1]
	v_pk_fma_f32 v[62:63], v[110:111], v[112:113], v[62:63] op_sel_hi:[1,0,1]
	v_add_f32_dpp v65, v64, v64 quad_perm:[1,0,3,2] row_mask:0xf bank_mask:0xf bound_ctrl:1
	v_cvt_pk_bf16_f32 v68, v2, v3
	v_cvt_pk_bf16_f32 v69, v4, v5
	v_add_f32_dpp v64, v65, v65 quad_perm:[2,3,0,1] row_mask:0xf bank_mask:0xf bound_ctrl:1
	ds_write_b64 v8, v[68:69] offset:23040
	ds_read_b128 v[80:83], v9 offset:16896
	v_add_f32_dpp v65, v64, v64 row_half_mirror row_mask:0xf bank_mask:0xf bound_ctrl:1
	ds_read_b128 v[76:79], v9 offset:16640
	ds_read_b128 v[88:91], v9 offset:17408
	v_add_f32_dpp v66, v65, v65 row_mirror row_mask:0xf bank_mask:0xf bound_ctrl:1
	v_pk_fma_f32 v[2:3], v[104:105], v[66:67], v[60:61] op_sel_hi:[1,0,1]
	v_pk_fma_f32 v[4:5], v[106:107], v[66:67], v[62:63] op_sel_hi:[1,0,1]
	ds_read_b32 v92, v10 offset:17664
	ds_read_b128 v[84:87], v9 offset:17152
	s_waitcnt lgkmcnt(6)
	v_pk_mul_f32 v[58:59], v[44:45], v[2:3]
	v_pk_mul_f32 v[60:61], v[40:41], v[2:3]
	v_pk_fma_f32 v[58:59], v[46:47], v[4:5], v[58:59]
	v_pk_mul_f32 v[62:63], v[42:43], v[4:5]
	v_add_f32_e32 v64, v58, v59
	v_pk_fma_f32 v[60:61], v[52:53], v[56:57], v[60:61] op_sel_hi:[1,0,1]
	v_pk_fma_f32 v[62:63], v[54:55], v[56:57], v[62:63] op_sel_hi:[1,0,1]
	v_add_f32_dpp v65, v64, v64 quad_perm:[1,0,3,2] row_mask:0xf bank_mask:0xf bound_ctrl:1
	v_cvt_pk_bf16_f32 v70, v2, v3
	v_cvt_pk_bf16_f32 v71, v4, v5
	v_add_f32_dpp v64, v65, v65 quad_perm:[2,3,0,1] row_mask:0xf bank_mask:0xf bound_ctrl:1
	ds_write_b64 v8, v[70:71] offset:25344
	ds_read_b128 v[100:103], v9 offset:18176
	v_add_f32_dpp v65, v64, v64 row_half_mirror row_mask:0xf bank_mask:0xf bound_ctrl:1
	ds_read_b128 v[96:99], v9 offset:17920
	ds_read_b128 v[108:111], v9 offset:18688
	v_add_f32_dpp v66, v65, v65 row_mirror row_mask:0xf bank_mask:0xf bound_ctrl:1
	v_pk_fma_f32 v[2:3], v[48:49], v[66:67], v[60:61] op_sel_hi:[1,0,1]
	v_pk_fma_f32 v[4:5], v[50:51], v[66:67], v[62:63] op_sel_hi:[1,0,1]
	ds_read_b32 v112, v10 offset:18944
	ds_read_b128 v[104:107], v9 offset:18432
	s_waitcnt lgkmcnt(6)
	v_pk_mul_f32 v[58:59], v[80:81], v[2:3]
	v_pk_mul_f32 v[60:61], v[76:77], v[2:3]
	v_pk_fma_f32 v[58:59], v[82:83], v[4:5], v[58:59]
	v_pk_mul_f32 v[62:63], v[78:79], v[4:5]
	v_add_f32_e32 v64, v58, v59
	v_pk_fma_f32 v[60:61], v[88:89], v[92:93], v[60:61] op_sel_hi:[1,0,1]
	v_pk_fma_f32 v[62:63], v[90:91], v[92:93], v[62:63] op_sel_hi:[1,0,1]
	v_add_f32_dpp v65, v64, v64 quad_perm:[1,0,3,2] row_mask:0xf bank_mask:0xf bound_ctrl:1
	v_cvt_pk_bf16_f32 v68, v2, v3
	v_cvt_pk_bf16_f32 v69, v4, v5
	v_add_f32_dpp v64, v65, v65 quad_perm:[2,3,0,1] row_mask:0xf bank_mask:0xf bound_ctrl:1
	ds_write_b64 v8, v[68:69] offset:27648
	ds_read_b128 v[44:47], v9 offset:19456
	v_add_f32_dpp v65, v64, v64 row_half_mirror row_mask:0xf bank_mask:0xf bound_ctrl:1
	ds_read_b128 v[40:43], v9 offset:19200
	ds_read_b128 v[52:55], v9 offset:19968
	v_add_f32_dpp v66, v65, v65 row_mirror row_mask:0xf bank_mask:0xf bound_ctrl:1
	v_pk_fma_f32 v[2:3], v[84:85], v[66:67], v[60:61] op_sel_hi:[1,0,1]
	v_pk_fma_f32 v[4:5], v[86:87], v[66:67], v[62:63] op_sel_hi:[1,0,1]
	ds_read_b32 v56, v10 offset:20224
	ds_read_b128 v[48:51], v9 offset:19712
	s_waitcnt lgkmcnt(6)
	v_pk_mul_f32 v[58:59], v[100:101], v[2:3]
	v_pk_mul_f32 v[60:61], v[96:97], v[2:3]
	v_pk_fma_f32 v[58:59], v[102:103], v[4:5], v[58:59]
	v_pk_mul_f32 v[62:63], v[98:99], v[4:5]
	v_add_f32_e32 v64, v58, v59
	v_pk_fma_f32 v[60:61], v[108:109], v[112:113], v[60:61] op_sel_hi:[1,0,1]
	v_pk_fma_f32 v[62:63], v[110:111], v[112:113], v[62:63] op_sel_hi:[1,0,1]
	v_add_f32_dpp v65, v64, v64 quad_perm:[1,0,3,2] row_mask:0xf bank_mask:0xf bound_ctrl:1
	v_cvt_pk_bf16_f32 v70, v2, v3
	v_cvt_pk_bf16_f32 v71, v4, v5
	v_add_f32_dpp v64, v65, v65 quad_perm:[2,3,0,1] row_mask:0xf bank_mask:0xf bound_ctrl:1
	ds_write_b64 v8, v[70:71] offset:29952
	s_nop 0
	v_add_f32_dpp v65, v64, v64 row_half_mirror row_mask:0xf bank_mask:0xf bound_ctrl:1
	s_nop 1
	v_add_f32_dpp v66, v65, v65 row_mirror row_mask:0xf bank_mask:0xf bound_ctrl:1
	v_pk_fma_f32 v[2:3], v[104:105], v[66:67], v[60:61] op_sel_hi:[1,0,1]
	v_pk_fma_f32 v[4:5], v[106:107], v[66:67], v[62:63] op_sel_hi:[1,0,1]
	s_waitcnt lgkmcnt(1)
	v_pk_mul_f32 v[58:59], v[44:45], v[2:3]
	v_pk_mul_f32 v[60:61], v[40:41], v[2:3]
	v_pk_fma_f32 v[58:59], v[46:47], v[4:5], v[58:59]
	v_pk_mul_f32 v[62:63], v[42:43], v[4:5]
	v_add_f32_e32 v64, v58, v59
	v_pk_fma_f32 v[60:61], v[52:53], v[56:57], v[60:61] op_sel_hi:[1,0,1]
	v_pk_fma_f32 v[62:63], v[54:55], v[56:57], v[62:63] op_sel_hi:[1,0,1]
	v_add_f32_dpp v65, v64, v64 quad_perm:[1,0,3,2] row_mask:0xf bank_mask:0xf bound_ctrl:1
	v_cvt_pk_bf16_f32 v68, v2, v3
	v_cvt_pk_bf16_f32 v69, v4, v5
	v_add_f32_dpp v64, v65, v65 quad_perm:[2,3,0,1] row_mask:0xf bank_mask:0xf bound_ctrl:1
	ds_write_b64 v8, v[68:69] offset:32256
	s_nop 0
	v_add_f32_dpp v65, v64, v64 row_half_mirror row_mask:0xf bank_mask:0xf bound_ctrl:1
	s_nop 1
	v_add_f32_dpp v66, v65, v65 row_mirror row_mask:0xf bank_mask:0xf bound_ctrl:1
	v_pk_fma_f32 v[2:3], v[48:49], v[66:67], v[60:61] op_sel_hi:[1,0,1]
	v_pk_fma_f32 v[4:5], v[50:51], v[66:67], v[62:63] op_sel_hi:[1,0,1]
	v_cvt_pk_bf16_f32 v70, v2, v3
	v_cvt_pk_bf16_f32 v71, v4, v5
	ds_write_b64 v8, v[70:71] offset:34560
	s_add_i32 s0, s0, 1
	s_cmpk_eq_i32 s0, 0x201
	s_waitcnt lgkmcnt(0)
	s_barrier
	s_cbranch_scc0 .LBB0_1047
	s_setprio 0
	s_mov_b64 s[0:1], 0

.LBB0_1111:
	s_or_b64 exec, exec, s[6:7]
	s_waitcnt lgkmcnt(0)
	s_barrier
	ds_read_b32 v2, v223
	s_mov_b64 s[6:7], -1
	s_waitcnt lgkmcnt(0)
	v_cmp_lt_u32_e32 vcc, s35, v2
	v_readfirstlane_b32 s10, v2
	s_cbranch_vccnz .LBB0_1106
	s_nop 0
	v_sub_co_u32_e32 v2, vcc, s10, v153
	s_and_b64 s[6:7], vcc, exec
	v_readfirstlane_b32 s0, v2
	s_cselect_b32 s0, s10, s0
	s_cselect_b32 s6, 41, 63
	s_lshr_b32 s0, s0, 3
	s_sub_i32 s11, s6, s0
	s_lshl_b32 s6, s11, 7
	s_or_b32 s60, s6, s64
	s_and_b32 s33, s10, 7
	s_or_b32 s7, s60, 16
	v_add_u32_e32 v224, s7, v147
	s_mul_i32 s0, s33, 0x2040
	v_add_u32_e32 v2, s0, v224
	v_lshlrev_b64 v[4:5], 8, v[2:3]
	v_or_b32_e32 v2, s0, v172
	s_lshl_b32 s61, s33, 7
	v_lshlrev_b32_e32 v2, 8, v2
	v_lshl_add_u64 v[6:7], v[180:181], 0, v[2:3]
	v_or_b32_e32 v2, s61, v168
	v_mad_u64_u32 v[192:193], s[30:31], v2, s62, v[184:185]
	v_or_b32_e32 v2, s0, v213
	v_lshlrev_b32_e32 v2, 8, v2
	v_or_b32_e32 v10, s61, v214
	v_lshl_add_u64 v[4:5], v[186:187], 0, v[4:5]
	v_lshl_add_u64 v[8:9], v[180:181], 0, v[2:3]
	v_mad_u64_u32 v[194:195], s[30:31], v10, s62, v[184:185]
	global_load_dwordx4 v[114:117], v[6:7], off
	global_load_dwordx4 v[138:141], v[192:193], off
	global_load_dwordx4 v[134:137], v[8:9], off
	global_load_dwordx4 v[142:145], v[194:195], off
	global_load_dwordx4 v[118:121], v[4:5], off
	global_load_dwordx4 v[122:125], v[4:5], off offset:32
	global_load_dwordx4 v[126:129], v[4:5], off offset:64
	global_load_dwordx4 v[130:133], v[4:5], off offset:96
	v_mov_b32_e32 v16, v3
	v_mov_b32_e32 v17, v3
	v_mov_b32_e32 v4, v3
	v_mov_b32_e32 v5, v3
	v_mov_b32_e32 v6, v3
	v_mov_b32_e32 v7, v3
	v_mov_b32_e32 v8, v3
	v_mov_b32_e32 v9, v3
	v_mov_b32_e32 v10, v3
	v_mov_b32_e32 v11, v3
	v_mov_b32_e32 v12, v3
	v_mov_b32_e32 v13, v3
	v_mov_b32_e32 v14, v3
	v_mov_b32_e32 v15, v3
	v_mad_u64_u32 v[196:197], s[30:31], s33, v159, v[190:191]
	s_lshl_b32 s11, s11, 1
	v_lshl_add_u64 v[198:199], v[188:189], 0, v[2:3]
	v_mov_b32_e32 v2, v3
	v_mov_b64_e32 v[32:33], v[16:17]
	v_mov_b64_e32 v[48:49], v[16:17]
	v_mov_b64_e32 v[64:65], v[16:17]
	v_mov_b64_e32 v[80:81], v[16:17]
	s_mov_b32 s68, 0
	v_mov_b32_e32 v226, 0xf149f2ca
	v_mov_b32_e32 v225, 0
	s_mov_b32 s0, 64
	s_add_i32 s11, s11, 3
	s_add_i32 s30, s60, 47
	v_mov_b64_e32 v[30:31], v[14:15]
	v_mov_b64_e32 v[28:29], v[12:13]
	v_mov_b64_e32 v[26:27], v[10:11]
	v_mov_b64_e32 v[24:25], v[8:9]
	v_mov_b64_e32 v[22:23], v[6:7]
	v_mov_b64_e32 v[20:21], v[4:5]
	v_mov_b64_e32 v[18:19], v[2:3]
	v_mov_b64_e32 v[46:47], v[14:15]
	v_mov_b64_e32 v[44:45], v[12:13]
	v_mov_b64_e32 v[42:43], v[10:11]
	v_mov_b64_e32 v[40:41], v[8:9]
	v_mov_b64_e32 v[38:39], v[6:7]
	v_mov_b64_e32 v[36:37], v[4:5]
	v_mov_b64_e32 v[34:35], v[2:3]
	v_mov_b64_e32 v[62:63], v[14:15]
	v_mov_b64_e32 v[60:61], v[12:13]
	v_mov_b64_e32 v[58:59], v[10:11]
	v_mov_b64_e32 v[56:57], v[8:9]
	v_mov_b64_e32 v[54:55], v[6:7]
	v_mov_b64_e32 v[52:53], v[4:5]
	v_mov_b64_e32 v[50:51], v[2:3]
	v_mov_b64_e32 v[78:79], v[14:15]
	v_mov_b64_e32 v[76:77], v[12:13]
	v_mov_b64_e32 v[74:75], v[10:11]
	v_mov_b64_e32 v[72:73], v[8:9]
	v_mov_b64_e32 v[70:71], v[6:7]
	v_mov_b64_e32 v[68:69], v[4:5]
	v_mov_b64_e32 v[66:67], v[2:3]
	s_waitcnt vmcnt(7)
	ds_write_b128 v220, v[114:117]
	s_waitcnt vmcnt(6)
	ds_write2_b64 v167, v[138:139], v[140:141] offset1:1
	s_waitcnt vmcnt(5)
	ds_write_b128 v221, v[134:137]
	s_waitcnt vmcnt(4)
	ds_write2_b64 v177, v[142:143], v[144:145] offset1:1
	s_waitcnt vmcnt(0) lgkmcnt(0)
	s_barrier

.LBB0_1115:
	s_sub_i32 s33, s0, 64
	s_cmp_gt_u32 s33, s30
	s_cbranch_scc1 .LBB0_1121
	s_bitcmp1_b32 s68, 0
	s_cselect_b32 s33, 0x8800, 0
	s_add_i32 s68, s33, 0
	s_add_i32 s33, s65, s68
	v_add3_u32 v2, s33, v165, v176
	ds_read_b128 v[4:7], v2
	ds_read_b128 v[8:11], v2 offset:32
	s_add_i32 s33, s0, -1
	s_cmp_le_u32 s33, s7
	s_waitcnt lgkmcnt(1)
	v_mfma_f32_32x32x16_bf16 v[98:113], v[4:7], v[118:121], 0
	ds_read_b128 v[4:7], v2 offset:8704
	ds_read_b128 v[12:15], v2 offset:8736
	s_waitcnt lgkmcnt(1)
	v_mfma_f32_32x32x16_bf16 v[82:97], v[4:7], v[118:121], 0
	v_mfma_f32_32x32x16_bf16 v[98:113], v[8:11], v[122:125], v[98:113]
	ds_read_b128 v[4:7], v2 offset:64
	ds_read_b128 v[8:11], v2 offset:96
	s_waitcnt lgkmcnt(2)
	v_mfma_f32_32x32x16_bf16 v[82:97], v[12:15], v[122:125], v[82:97]
	s_waitcnt lgkmcnt(1)
	v_mfma_f32_32x32x16_bf16 v[98:113], v[4:7], v[126:129], v[98:113]
	ds_read_b128 v[4:7], v2 offset:8768
	ds_read_b128 v[12:15], v2 offset:8800
	s_waitcnt lgkmcnt(1)
	v_mfma_f32_32x32x16_bf16 v[82:97], v[4:7], v[126:129], v[82:97]
	v_mfma_f32_32x32x16_bf16 v[98:113], v[8:11], v[130:133], v[98:113]
	s_waitcnt lgkmcnt(0)
	v_mfma_f32_32x32x16_bf16 v[82:97], v[12:15], v[130:133], v[82:97]
	s_cbranch_scc1 .LBB0_1118
	v_add_u32_e32 v2, s0, v178
	v_subrev_u32_e32 v5, 32, v2
	v_subrev_u32_e32 v4, 64, v2
	v_cmp_le_u32_e32 vcc, v5, v224
	s_nop 6
	v_cndmask_b32_e32 v82, v161, v82, vcc
	v_cmp_lt_u32_e32 vcc, v4, v224
	s_nop 1
	v_cndmask_b32_e32 v99, v161, v99, vcc
	v_cmp_le_u32_e32 vcc, v4, v224
	v_subrev_u32_e32 v4, 31, v2
	s_nop 0
	v_cndmask_b32_e32 v98, v161, v98, vcc
	v_cmp_le_u32_e32 vcc, v4, v224
	v_subrev_u32_e32 v4, 62, v2
	s_nop 0
	v_cndmask_b32_e32 v83, v161, v83, vcc
	v_cmp_le_u32_e32 vcc, v4, v224
	v_subrev_u32_e32 v4, 30, v2
	s_nop 0
	v_cndmask_b32_e32 v100, v161, v100, vcc
	v_cmp_le_u32_e32 vcc, v4, v224
	v_subrev_u32_e32 v4, 61, v2
	s_nop 0
	v_cndmask_b32_e32 v84, v161, v84, vcc
	v_cmp_le_u32_e32 vcc, v4, v224
	v_subrev_u32_e32 v4, 29, v2
	s_nop 0
	v_cndmask_b32_e32 v101, v161, v101, vcc
	v_cmp_le_u32_e32 vcc, v4, v224
	v_subrev_u32_e32 v4, 56, v2
	s_nop 0
	v_cndmask_b32_e32 v85, v161, v85, vcc
	v_cmp_le_u32_e32 vcc, v4, v224
	v_subrev_u32_e32 v4, 24, v2
	s_nop 0
	v_cndmask_b32_e32 v102, v161, v102, vcc
	v_cmp_le_u32_e32 vcc, v4, v224
	v_subrev_u32_e32 v4, 55, v2
	s_nop 0
	v_cndmask_b32_e32 v86, v161, v86, vcc
	v_cmp_le_u32_e32 vcc, v4, v224
	v_subrev_u32_e32 v4, 23, v2
	s_nop 0
	v_cndmask_b32_e32 v103, v161, v103, vcc
	v_cmp_le_u32_e32 vcc, v4, v224
	v_subrev_u32_e32 v4, 54, v2
	s_nop 0
	v_cndmask_b32_e32 v87, v161, v87, vcc
	v_cmp_le_u32_e32 vcc, v4, v224
	v_subrev_u32_e32 v4, 22, v2
	s_nop 0
	v_cndmask_b32_e32 v104, v161, v104, vcc
	v_cmp_le_u32_e32 vcc, v4, v224
	v_subrev_u32_e32 v4, 53, v2
	s_nop 0
	v_cndmask_b32_e32 v88, v161, v88, vcc
	v_cmp_le_u32_e32 vcc, v4, v224
	v_subrev_u32_e32 v4, 21, v2
	s_nop 0
	v_cndmask_b32_e32 v105, v161, v105, vcc
	v_cmp_le_u32_e32 vcc, v4, v224
	v_subrev_u32_e32 v4, 48, v2
	s_nop 0
	v_cndmask_b32_e32 v89, v161, v89, vcc
	v_cmp_le_u32_e32 vcc, v4, v224
	v_add_u32_e32 v4, -16, v2
	s_nop 0
	v_cndmask_b32_e32 v106, v161, v106, vcc
	v_cmp_le_u32_e32 vcc, v4, v224
	v_subrev_u32_e32 v4, 47, v2
	s_nop 0
	v_cndmask_b32_e32 v90, v161, v90, vcc
	v_cmp_le_u32_e32 vcc, v4, v224
	v_add_u32_e32 v4, -15, v2
	s_nop 0
	v_cndmask_b32_e32 v107, v161, v107, vcc
	v_cmp_le_u32_e32 vcc, v4, v224
	v_subrev_u32_e32 v4, 46, v2
	s_nop 0
	v_cndmask_b32_e32 v91, v161, v91, vcc
	v_cmp_le_u32_e32 vcc, v4, v224
	v_add_u32_e32 v4, -14, v2
	s_nop 0
	v_cndmask_b32_e32 v108, v161, v108, vcc
	v_cmp_le_u32_e32 vcc, v4, v224
	v_subrev_u32_e32 v4, 45, v2
	s_nop 0
	v_cndmask_b32_e32 v92, v161, v92, vcc
	v_cmp_le_u32_e32 vcc, v4, v224
	v_add_u32_e32 v4, -13, v2
	s_nop 0
	v_cndmask_b32_e32 v109, v161, v109, vcc
	v_cmp_le_u32_e32 vcc, v4, v224
	v_subrev_u32_e32 v4, 40, v2
	s_nop 0
	v_cndmask_b32_e32 v93, v161, v93, vcc
	v_cmp_le_u32_e32 vcc, v4, v224
	v_add_u32_e32 v4, -8, v2
	s_nop 0
	v_cndmask_b32_e32 v110, v161, v110, vcc
	v_cmp_le_u32_e32 vcc, v4, v224
	v_subrev_u32_e32 v4, 39, v2
	s_nop 0
	v_cndmask_b32_e32 v94, v161, v94, vcc
	v_cmp_le_u32_e32 vcc, v4, v224
	v_add_u32_e32 v4, -7, v2
	s_nop 0
	v_cndmask_b32_e32 v111, v161, v111, vcc
	v_cmp_le_u32_e32 vcc, v4, v224
	v_subrev_u32_e32 v4, 38, v2
	s_nop 0
	v_cndmask_b32_e32 v95, v161, v95, vcc
	v_cmp_le_u32_e32 vcc, v4, v224
	v_add_u32_e32 v4, -6, v2
	s_nop 0
	v_cndmask_b32_e32 v112, v161, v112, vcc
	v_cmp_le_u32_e32 vcc, v4, v224
	v_subrev_u32_e32 v4, 37, v2
	v_add_u32_e32 v2, -5, v2
	v_cndmask_b32_e32 v96, v161, v96, vcc
	v_cmp_le_u32_e32 vcc, v4, v224
	s_nop 1
	v_cndmask_b32_e32 v113, v161, v113, vcc
	v_cmp_le_u32_e32 vcc, v2, v224
	s_nop 1
	v_cndmask_b32_e32 v97, v161, v97, vcc
